# non-temporal hint on the up-projection's h stores (streaming 268 MB per layer) to protect the operand panels in L2
# baseline (speedup 1.0000x reference)
; __device__ __forceinline__ u32x4 pack8(f32x4 a, f32x4 b) { u32x4 w; w.x = cvt_pk_bf16(a[0], a[1]); w.y = cvt_pk_bf16(a[2], a[3]); w.z = cvt_pk_bf16(b[0], b[1]); w.w = cvt_pk_bf16(b[2], b[3]); return w; }
;     __device__ __forceinline__ void operator()(const f32x4 (&acc)[2][2][4][2], const Unit& u, int wr, int wc, int fr, int fq) const {
;     ...
;         for (int ai = 0; ai < 2; ++ai)
; #pragma unroll
;             for (int m = 0; m < 4; ++m) {
;                 const int row = u.pm * 256 + ai * 128 + wr * 64 + m * 16 + fr;
; #pragma unroll
;                 for (int bj = 0; bj < 2; ++bj) {
;                     f32x4 v0 = acc[ai][bj][m][0], v1 = acc[ai][bj][m][1];
; #pragma unroll
;                     for (int i = 0; i < 4; ++i) { const float a = fmaxf(v0[i], 0.f), b = fmaxf(v1[i], 0.f); v0[i] = a * a; v1[i] = b * b; }
;                     *(u32x4*)(H + (size_t)row * FF + colb + bj * 128) = pack8(v0, v1);
;                 }
.LBB0_1462:
	v_lshl_add_u32 v140, s56, 8, v142
	v_ashrrev_i32_e32 v141, 31, v140
	v_max_f32_e32 v124, 0, v124
	v_lshlrev_b64 v[148:149], 13, v[140:141]
	v_mul_f32_e32 v141, v124, v124
	v_lshl_or_b32 v146, s72, 8, v144
	v_max_f32_e32 v126, 0, v126
	v_max_f32_e32 v122, 0, v122
	v_max_f32_e32 v123, 0, v123
	v_max_f32_e32 v128, 0, v128
	v_max_f32_e32 v124, 0, v129
	v_ashrrev_i32_e32 v147, 31, v146
	v_mul_f32_e32 v126, v126, v126
	v_mul_f32_e32 v122, v122, v122
	v_max_f32_e32 v127, 0, v127
	v_mul_f32_e32 v123, v123, v123
	v_mul_f32_e32 v128, v128, v128
	v_max_f32_e32 v125, 0, v125
	v_mul_f32_e32 v129, v124, v124
	v_mul_f32_e32 v127, v127, v127
	v_mul_f32_e32 v150, v125, v125
	v_cvt_pk_bf16_f32 v124, v126, v127
	v_cvt_pk_bf16_f32 v125, v128, v129
	v_cvt_pk_bf16_f32 v126, v122, v123
	v_lshl_add_u64 v[128:129], s[18:19], 0, v[148:149]
	v_lshlrev_b64 v[122:123], 1, v[146:147]
	v_lshl_add_u64 v[128:129], v[128:129], 0, v[122:123]
	v_max_f32_e32 v114, 0, v114
	v_max_f32_e32 v115, 0, v115
	v_max_f32_e32 v116, 0, v116
	v_cvt_pk_bf16_f32 v127, v141, v150
	global_store_dwordx4 v[128:129], v[124:127], off nt
	s_nop 1
	v_mul_f32_e32 v124, v114, v114
	v_max_f32_e32 v114, v119, v119
	v_mul_f32_e32 v119, v115, v115
	v_max_f32_e32 v115, v120, v120
	v_mul_f32_e32 v120, v116, v116
	v_max_f32_e32 v114, 0, v114
	v_max_f32_e32 v115, 0, v115
	v_max_f32_e32 v116, 0, v121
	v_max_f32_e32 v118, 0, v118
	v_mul_f32_e32 v114, v114, v114
	v_mul_f32_e32 v115, v115, v115
	v_max_f32_e32 v117, 0, v117
	v_mul_f32_e32 v116, v116, v116
	v_mul_f32_e32 v118, v118, v118
	v_mul_f32_e32 v117, v117, v117
	v_cvt_pk_bf16_f32 v114, v118, v114
	v_cvt_pk_bf16_f32 v115, v115, v116
	v_cvt_pk_bf16_f32 v116, v124, v119
	v_max_f32_e32 v106, 0, v106
	v_max_f32_e32 v107, 0, v107
	v_max_f32_e32 v108, 0, v108
	v_cvt_pk_bf16_f32 v117, v120, v117
	global_store_dwordx4 v[128:129], v[114:117], off offset:256 nt
	s_nop 1
	v_max_f32_e32 v110, 0, v110
	v_or_b32_e32 v114, 16, v140
	v_mul_f32_e32 v116, v106, v106
	v_max_f32_e32 v106, v111, v111
	v_mul_f32_e32 v111, v107, v107
	v_max_f32_e32 v107, v112, v112
	v_mul_f32_e32 v112, v108, v108
	v_ashrrev_i32_e32 v115, 31, v114
	v_max_f32_e32 v106, 0, v106
	v_max_f32_e32 v107, 0, v107
	v_max_f32_e32 v108, 0, v113
	v_lshlrev_b64 v[114:115], 13, v[114:115]
	v_mul_f32_e32 v110, v110, v110
	v_mul_f32_e32 v106, v106, v106
	v_mul_f32_e32 v107, v107, v107
	v_mul_f32_e32 v108, v108, v108
	v_max_f32_e32 v109, 0, v109
	v_cvt_pk_bf16_f32 v106, v110, v106
	v_cvt_pk_bf16_f32 v107, v107, v108
	v_cvt_pk_bf16_f32 v108, v116, v111
	v_lshl_add_u64 v[110:111], s[18:19], 0, v[114:115]
	v_mul_f32_e32 v109, v109, v109
	v_lshl_add_u64 v[110:111], v[110:111], 0, v[122:123]
	v_max_f32_e32 v98, 0, v98
	v_max_f32_e32 v99, 0, v99
	v_max_f32_e32 v100, 0, v100
	v_cvt_pk_bf16_f32 v109, v112, v109
	global_store_dwordx4 v[110:111], v[106:109], off nt
	s_nop 1
	v_mul_f32_e32 v106, v98, v98
	v_max_f32_e32 v98, v103, v103
	v_mul_f32_e32 v103, v99, v99
	v_max_f32_e32 v99, v104, v104
	v_mul_f32_e32 v104, v100, v100
	v_max_f32_e32 v98, 0, v98
	v_max_f32_e32 v99, 0, v99
	v_max_f32_e32 v100, 0, v105
	v_max_f32_e32 v102, 0, v102
	v_mul_f32_e32 v98, v98, v98
	v_mul_f32_e32 v99, v99, v99
	v_max_f32_e32 v101, 0, v101
	v_mul_f32_e32 v100, v100, v100
	v_mul_f32_e32 v102, v102, v102
	v_mul_f32_e32 v101, v101, v101
	v_cvt_pk_bf16_f32 v98, v102, v98
	v_cvt_pk_bf16_f32 v99, v99, v100
	v_cvt_pk_bf16_f32 v100, v106, v103
	v_max_f32_e32 v90, 0, v90
	v_max_f32_e32 v91, 0, v91
	v_max_f32_e32 v92, 0, v92
	v_cvt_pk_bf16_f32 v101, v104, v101
	global_store_dwordx4 v[110:111], v[98:101], off offset:256 nt
	s_nop 1
	v_max_f32_e32 v94, 0, v94
	v_or_b32_e32 v98, 32, v140
	v_mul_f32_e32 v100, v90, v90
	v_max_f32_e32 v90, v95, v95
	v_mul_f32_e32 v95, v91, v91
	v_max_f32_e32 v91, v96, v96
	v_mul_f32_e32 v96, v92, v92
	v_ashrrev_i32_e32 v99, 31, v98
	v_max_f32_e32 v90, 0, v90
	v_max_f32_e32 v91, 0, v91
	v_max_f32_e32 v92, 0, v97
	v_lshlrev_b64 v[98:99], 13, v[98:99]
	v_mul_f32_e32 v94, v94, v94
	v_mul_f32_e32 v90, v90, v90
	v_mul_f32_e32 v91, v91, v91
	v_mul_f32_e32 v92, v92, v92
	v_max_f32_e32 v93, 0, v93
	v_cvt_pk_bf16_f32 v90, v94, v90
	v_cvt_pk_bf16_f32 v91, v91, v92
	v_cvt_pk_bf16_f32 v92, v100, v95
	v_lshl_add_u64 v[94:95], s[18:19], 0, v[98:99]
	v_mul_f32_e32 v93, v93, v93
	v_lshl_add_u64 v[94:95], v[94:95], 0, v[122:123]
	v_max_f32_e32 v82, 0, v82
	v_max_f32_e32 v83, 0, v83
	v_max_f32_e32 v84, 0, v84
	v_cvt_pk_bf16_f32 v93, v96, v93
	global_store_dwordx4 v[94:95], v[90:93], off nt
	s_nop 1
	v_mul_f32_e32 v90, v82, v82
	v_max_f32_e32 v82, v87, v87
	v_mul_f32_e32 v87, v83, v83
	v_max_f32_e32 v83, v88, v88
	v_mul_f32_e32 v88, v84, v84
	v_max_f32_e32 v82, 0, v82
	v_max_f32_e32 v83, 0, v83
	v_max_f32_e32 v84, 0, v89
	v_max_f32_e32 v86, 0, v86
	v_mul_f32_e32 v82, v82, v82
	v_mul_f32_e32 v83, v83, v83
	v_max_f32_e32 v85, 0, v85
	v_mul_f32_e32 v84, v84, v84
	v_mul_f32_e32 v86, v86, v86
	v_mul_f32_e32 v85, v85, v85
	v_cvt_pk_bf16_f32 v82, v86, v82
	v_cvt_pk_bf16_f32 v83, v83, v84
	v_cvt_pk_bf16_f32 v84, v90, v87
	v_max_f32_e32 v74, 0, v74
	v_max_f32_e32 v75, 0, v75
	v_max_f32_e32 v76, 0, v76
	v_cvt_pk_bf16_f32 v85, v88, v85
	global_store_dwordx4 v[94:95], v[82:85], off offset:256 nt
	s_nop 1
	v_max_f32_e32 v78, 0, v78
	v_or_b32_e32 v82, 48, v140
	v_mul_f32_e32 v84, v74, v74
	v_max_f32_e32 v74, v79, v79
	v_mul_f32_e32 v79, v75, v75
	v_max_f32_e32 v75, v80, v80
	v_mul_f32_e32 v80, v76, v76
	v_ashrrev_i32_e32 v83, 31, v82
	v_max_f32_e32 v74, 0, v74
	v_max_f32_e32 v75, 0, v75
	v_max_f32_e32 v76, 0, v81
	v_lshlrev_b64 v[82:83], 13, v[82:83]
	v_mul_f32_e32 v78, v78, v78
	v_mul_f32_e32 v74, v74, v74
	v_mul_f32_e32 v75, v75, v75
; __device__ __forceinline__ u32x4 pack8(f32x4 a, f32x4 b) { u32x4 w; w.x = cvt_pk_bf16(a[0], a[1]); w.y = cvt_pk_bf16(a[2], a[3]); w.z = cvt_pk_bf16(b[0], b[1]); w.w = cvt_pk_bf16(b[2], b[3]); return w; }
;     __device__ __forceinline__ void operator()(const f32x4 (&acc)[2][2][4][2], const Unit& u, int wr, int wc, int fr, int fq) const {
;     ...
;         for (int ai = 0; ai < 2; ++ai)
; #pragma unroll
;             for (int m = 0; m < 4; ++m) {
;                 const int row = u.pm * 256 + ai * 128 + wr * 64 + m * 16 + fr;
; #pragma unroll
;                 for (int bj = 0; bj < 2; ++bj) {
;                     f32x4 v0 = acc[ai][bj][m][0], v1 = acc[ai][bj][m][1];
; #pragma unroll
;                     for (int i = 0; i < 4; ++i) { const float a = fmaxf(v0[i], 0.f), b = fmaxf(v1[i], 0.f); v0[i] = a * a; v1[i] = b * b; }
;                     *(u32x4*)(H + (size_t)row * FF + colb + bj * 128) = pack8(v0, v1);
;                 }
	v_mul_f32_e32 v76, v76, v76
	v_max_f32_e32 v77, 0, v77
	v_cvt_pk_bf16_f32 v74, v78, v74
	v_cvt_pk_bf16_f32 v75, v75, v76
	v_cvt_pk_bf16_f32 v76, v84, v79
	v_lshl_add_u64 v[78:79], s[18:19], 0, v[82:83]
	v_mul_f32_e32 v77, v77, v77
	v_lshl_add_u64 v[78:79], v[78:79], 0, v[122:123]
	v_max_f32_e32 v66, 0, v66
	v_max_f32_e32 v67, 0, v67
	v_max_f32_e32 v68, 0, v68
	v_cvt_pk_bf16_f32 v77, v80, v77
	global_store_dwordx4 v[78:79], v[74:77], off nt
	s_nop 1
	v_mul_f32_e32 v74, v66, v66
	v_max_f32_e32 v66, v71, v71
	v_mul_f32_e32 v71, v67, v67
	v_max_f32_e32 v67, v72, v72
	v_mul_f32_e32 v72, v68, v68
	v_max_f32_e32 v66, 0, v66
	v_max_f32_e32 v67, 0, v67
	v_max_f32_e32 v68, 0, v73
	v_max_f32_e32 v70, 0, v70
	v_mul_f32_e32 v66, v66, v66
	v_mul_f32_e32 v67, v67, v67
	v_max_f32_e32 v69, 0, v69
	v_mul_f32_e32 v68, v68, v68
	v_mul_f32_e32 v70, v70, v70
	v_mul_f32_e32 v69, v69, v69
	v_cvt_pk_bf16_f32 v66, v70, v66
	v_cvt_pk_bf16_f32 v67, v67, v68
	v_cvt_pk_bf16_f32 v68, v74, v71
	v_max_f32_e32 v58, 0, v58
	v_max_f32_e32 v59, 0, v59
	v_max_f32_e32 v60, 0, v60
	v_cvt_pk_bf16_f32 v69, v72, v69
	global_store_dwordx4 v[78:79], v[66:69], off offset:256 nt
	s_nop 1
	v_max_f32_e32 v62, 0, v62
	v_add_u32_e32 v66, 0x80, v140
	v_mul_f32_e32 v68, v58, v58
	v_max_f32_e32 v58, v63, v63
	v_mul_f32_e32 v63, v59, v59
	v_max_f32_e32 v59, v64, v64
	v_mul_f32_e32 v64, v60, v60
	v_ashrrev_i32_e32 v67, 31, v66
	v_max_f32_e32 v58, 0, v58
	v_max_f32_e32 v59, 0, v59
	v_max_f32_e32 v60, 0, v65
	v_lshlrev_b64 v[66:67], 13, v[66:67]
	v_mul_f32_e32 v62, v62, v62
	v_mul_f32_e32 v58, v58, v58
	v_mul_f32_e32 v59, v59, v59
	v_mul_f32_e32 v60, v60, v60
	v_max_f32_e32 v61, 0, v61
	v_cvt_pk_bf16_f32 v58, v62, v58
	v_cvt_pk_bf16_f32 v59, v59, v60
	v_cvt_pk_bf16_f32 v60, v68, v63
	v_lshl_add_u64 v[62:63], s[18:19], 0, v[66:67]
	v_mul_f32_e32 v61, v61, v61
	v_lshl_add_u64 v[62:63], v[62:63], 0, v[122:123]
	v_max_f32_e32 v50, 0, v50
	v_max_f32_e32 v51, 0, v51
	v_max_f32_e32 v52, 0, v52
	v_cvt_pk_bf16_f32 v61, v64, v61
	global_store_dwordx4 v[62:63], v[58:61], off nt
	s_nop 1
	v_mul_f32_e32 v58, v50, v50
	v_max_f32_e32 v50, v55, v55
	v_mul_f32_e32 v55, v51, v51
	v_max_f32_e32 v51, v56, v56
	v_mul_f32_e32 v56, v52, v52
	v_max_f32_e32 v50, 0, v50
	v_max_f32_e32 v51, 0, v51
	v_max_f32_e32 v52, 0, v57
	v_max_f32_e32 v54, 0, v54
	v_mul_f32_e32 v50, v50, v50
	v_mul_f32_e32 v51, v51, v51
	v_max_f32_e32 v53, 0, v53
	v_mul_f32_e32 v52, v52, v52
	v_mul_f32_e32 v54, v54, v54
	v_mul_f32_e32 v53, v53, v53
	v_cvt_pk_bf16_f32 v50, v54, v50
	v_cvt_pk_bf16_f32 v51, v51, v52
	v_cvt_pk_bf16_f32 v52, v58, v55
	v_max_f32_e32 v42, 0, v42
	v_max_f32_e32 v43, 0, v43
	v_max_f32_e32 v44, 0, v44
	v_cvt_pk_bf16_f32 v53, v56, v53
	global_store_dwordx4 v[62:63], v[50:53], off offset:256 nt
	s_nop 1
	v_max_f32_e32 v46, 0, v46
	v_add_u32_e32 v50, 0x90, v140
	v_mul_f32_e32 v52, v42, v42
	v_max_f32_e32 v42, v47, v47
	v_mul_f32_e32 v47, v43, v43
	v_max_f32_e32 v43, v48, v48
	v_mul_f32_e32 v48, v44, v44
	v_ashrrev_i32_e32 v51, 31, v50
	v_max_f32_e32 v42, 0, v42
	v_max_f32_e32 v43, 0, v43
	v_max_f32_e32 v44, 0, v49
	v_lshlrev_b64 v[50:51], 13, v[50:51]
	v_mul_f32_e32 v46, v46, v46
	v_mul_f32_e32 v42, v42, v42
	v_mul_f32_e32 v43, v43, v43
	v_mul_f32_e32 v44, v44, v44
	v_max_f32_e32 v45, 0, v45
	v_cvt_pk_bf16_f32 v42, v46, v42
	v_cvt_pk_bf16_f32 v43, v43, v44
	v_cvt_pk_bf16_f32 v44, v52, v47
	v_lshl_add_u64 v[46:47], s[18:19], 0, v[50:51]
	v_mul_f32_e32 v45, v45, v45
	v_lshl_add_u64 v[46:47], v[46:47], 0, v[122:123]
	v_max_f32_e32 v34, 0, v34
	v_max_f32_e32 v35, 0, v35
	v_max_f32_e32 v36, 0, v36
	v_cvt_pk_bf16_f32 v45, v48, v45
	global_store_dwordx4 v[46:47], v[42:45], off nt
	s_nop 1
	v_mul_f32_e32 v42, v34, v34
	v_max_f32_e32 v34, v39, v39
	v_mul_f32_e32 v39, v35, v35
	v_max_f32_e32 v35, v40, v40
	v_mul_f32_e32 v40, v36, v36
; #define PG8_BAR __builtin_amdgcn_s_barrier()
; __device__ __forceinline__ u32x4 pack8(f32x4 a, f32x4 b) { u32x4 w; w.x = cvt_pk_bf16(a[0], a[1]); w.y = cvt_pk_bf16(a[2], a[3]); w.z = cvt_pk_bf16(b[0], b[1]); w.w = cvt_pk_bf16(b[2], b[3]); return w; }
; template <class Epi, bool MID = false>
; __device__ __forceinline__ void gemm_phase(LAS unsigned char* lds, const Gemm g, const StaticOrder& S, const Epi& E) {
;     ...
;         if (wr == 1) PG8_BAR;
;     __device__ __forceinline__ void operator()(const f32x4 (&acc)[2][2][4][2], const Unit& u, int wr, int wc, int fr, int fq) const {
;     ...
;         for (int ai = 0; ai < 2; ++ai)
; #pragma unroll
;             for (int m = 0; m < 4; ++m) {
;                 const int row = u.pm * 256 + ai * 128 + wr * 64 + m * 16 + fr;
; #pragma unroll
;                 for (int bj = 0; bj < 2; ++bj) {
;                     f32x4 v0 = acc[ai][bj][m][0], v1 = acc[ai][bj][m][1];
; #pragma unroll
;                     for (int i = 0; i < 4; ++i) { const float a = fmaxf(v0[i], 0.f), b = fmaxf(v1[i], 0.f); v0[i] = a * a; v1[i] = b * b; }
;                     *(u32x4*)(H + (size_t)row * FF + colb + bj * 128) = pack8(v0, v1);
;                 }
	v_max_f32_e32 v34, 0, v34
	v_max_f32_e32 v35, 0, v35
	v_max_f32_e32 v36, 0, v41
	v_max_f32_e32 v38, 0, v38
	v_mul_f32_e32 v34, v34, v34
	v_mul_f32_e32 v35, v35, v35
	v_max_f32_e32 v37, 0, v37
	v_mul_f32_e32 v36, v36, v36
	v_mul_f32_e32 v38, v38, v38
	v_mul_f32_e32 v37, v37, v37
	v_cvt_pk_bf16_f32 v34, v38, v34
	v_cvt_pk_bf16_f32 v35, v35, v36
	v_cvt_pk_bf16_f32 v36, v42, v39
	v_max_f32_e32 v26, 0, v26
	v_max_f32_e32 v27, 0, v27
	v_max_f32_e32 v28, 0, v28
	v_cvt_pk_bf16_f32 v37, v40, v37
	global_store_dwordx4 v[46:47], v[34:37], off offset:256 nt
	s_nop 1
	v_max_f32_e32 v30, 0, v30
	v_add_u32_e32 v34, 0xa0, v140
	v_mul_f32_e32 v36, v26, v26
	v_max_f32_e32 v26, v31, v31
	v_mul_f32_e32 v31, v27, v27
	v_max_f32_e32 v27, v32, v32
	v_mul_f32_e32 v32, v28, v28
	v_ashrrev_i32_e32 v35, 31, v34
	v_max_f32_e32 v26, 0, v26
	v_max_f32_e32 v27, 0, v27
	v_max_f32_e32 v28, 0, v33
	v_lshlrev_b64 v[34:35], 13, v[34:35]
	v_mul_f32_e32 v30, v30, v30
	v_mul_f32_e32 v26, v26, v26
	v_mul_f32_e32 v27, v27, v27
	v_mul_f32_e32 v28, v28, v28
	v_max_f32_e32 v29, 0, v29
	v_cvt_pk_bf16_f32 v26, v30, v26
	v_cvt_pk_bf16_f32 v27, v27, v28
	v_cvt_pk_bf16_f32 v28, v36, v31
	v_lshl_add_u64 v[30:31], s[18:19], 0, v[34:35]
	v_mul_f32_e32 v29, v29, v29
	v_lshl_add_u64 v[30:31], v[30:31], 0, v[122:123]
	v_max_f32_e32 v18, 0, v18
	v_max_f32_e32 v19, 0, v19
	v_max_f32_e32 v20, 0, v20
	v_cvt_pk_bf16_f32 v29, v32, v29
	global_store_dwordx4 v[30:31], v[26:29], off nt
	s_nop 1
	v_mul_f32_e32 v26, v18, v18
	v_max_f32_e32 v18, v23, v23
	v_mul_f32_e32 v23, v19, v19
	v_max_f32_e32 v19, v24, v24
	v_mul_f32_e32 v24, v20, v20
	v_max_f32_e32 v18, 0, v18
	v_max_f32_e32 v19, 0, v19
	v_max_f32_e32 v20, 0, v25
	v_max_f32_e32 v22, 0, v22
	v_mul_f32_e32 v18, v18, v18
	v_mul_f32_e32 v19, v19, v19
	v_max_f32_e32 v21, 0, v21
	v_mul_f32_e32 v20, v20, v20
	v_mul_f32_e32 v22, v22, v22
	v_mul_f32_e32 v21, v21, v21
	v_cvt_pk_bf16_f32 v18, v22, v18
	v_cvt_pk_bf16_f32 v19, v19, v20
	v_cvt_pk_bf16_f32 v20, v26, v23
	v_max_f32_e32 v10, 0, v10
	v_max_f32_e32 v11, 0, v11
	v_max_f32_e32 v12, 0, v12
	v_cvt_pk_bf16_f32 v21, v24, v21
	global_store_dwordx4 v[30:31], v[18:21], off offset:256 nt
	s_nop 1
	v_max_f32_e32 v14, 0, v14
	v_add_u32_e32 v18, 0xb0, v140
	v_mul_f32_e32 v20, v10, v10
	v_max_f32_e32 v10, v15, v15
	v_mul_f32_e32 v15, v11, v11
	v_max_f32_e32 v11, v16, v16
	v_mul_f32_e32 v16, v12, v12
	v_ashrrev_i32_e32 v19, 31, v18
	v_max_f32_e32 v10, 0, v10
	v_max_f32_e32 v11, 0, v11
	v_max_f32_e32 v12, 0, v17
	v_lshlrev_b64 v[18:19], 13, v[18:19]
	v_mul_f32_e32 v14, v14, v14
	v_mul_f32_e32 v10, v10, v10
	v_mul_f32_e32 v11, v11, v11
	v_mul_f32_e32 v12, v12, v12
	v_max_f32_e32 v13, 0, v13
	v_cvt_pk_bf16_f32 v10, v14, v10
	v_cvt_pk_bf16_f32 v11, v11, v12
	v_cvt_pk_bf16_f32 v12, v20, v15
	v_lshl_add_u64 v[14:15], s[18:19], 0, v[18:19]
	v_mul_f32_e32 v13, v13, v13
	v_lshl_add_u64 v[14:15], v[14:15], 0, v[122:123]
	v_max_f32_e32 v2, 0, v2
	v_max_f32_e32 v3, 0, v3
	v_max_f32_e32 v4, 0, v4
	v_cvt_pk_bf16_f32 v13, v16, v13
	global_store_dwordx4 v[14:15], v[10:13], off nt
	s_nop 1
	v_mul_f32_e32 v10, v2, v2
	v_max_f32_e32 v2, v7, v7
	v_mul_f32_e32 v7, v3, v3
	v_max_f32_e32 v3, v8, v8
	v_mul_f32_e32 v8, v4, v4
	v_max_f32_e32 v2, 0, v2
	v_max_f32_e32 v3, 0, v3
	v_max_f32_e32 v4, 0, v9
	v_max_f32_e32 v5, 0, v5
	v_max_f32_e32 v6, 0, v6
	v_mul_f32_e32 v2, v2, v2
	v_mul_f32_e32 v3, v3, v3
	v_mul_f32_e32 v4, v4, v4
	v_mul_f32_e32 v5, v5, v5
	s_andn2_b64 vcc, exec, s[38:39]
	s_mov_b64 s[38:39], -1
	v_mul_f32_e32 v6, v6, v6
	v_cvt_pk_bf16_f32 v2, v6, v2
	v_cvt_pk_bf16_f32 v3, v3, v4
	v_cvt_pk_bf16_f32 v4, v10, v7
	v_cvt_pk_bf16_f32 v5, v8, v5
	global_store_dwordx4 v[14:15], v[2:5], off offset:256 nt
	s_nop 1
	s_cbranch_vccnz .LBB0_1450
	s_andn2_b64 vcc, exec, s[0:1]
	s_cbranch_vccnz .LBB0_1449
	s_barrier
	s_branch .LBB0_1449
